# FFN-up loop: fragments read at step top, LDS-DMA gets two full steps to land (vmcnt(6) instead of 0)
# speedup vs baseline: 1.0573x; 1.0040x over previous
.Lhw_ffnup_dloop:
	s_cmp_ge_u32 s2, s64
	s_cbranch_scc1 .Lhw_ffnup_tail
	s_mul_i32 s6, s2, 745
	s_lshr_b32 s6, s6, 16
	s_mul_i32 s14, s6, 88
	s_sub_i32 s14, s2, s14
	v_readlane_b32 s13, v246, 16
	s_lshl_b32 s6, s6, 2
	s_and_b32 s12, s14, 3
	s_add_i32 s6, s6, s12
	s_add_i32 s6, s6, s13
	s_lshl_b32 s6, s6, 7
	s_lshr_b32 s14, s14, 2
	s_lshl_b32 s14, s14, 8
	s_lshl_b32 vcc_lo, s6, 11
	s_add_u32 s66, s10, vcc_lo
	s_addc_u32 s67, s11, 0
	s_lshl_b32 vcc_lo, s14, 11
	s_add_u32 s12, s0, vcc_lo
	s_addc_u32 s13, s1, 0
	s_add_u32 s62, s12, 0x40000
	s_addc_u32 s63, s13, 0
	s_barrier
	s_add_u32 m0, s65, 0x0
	s_nop 0
	global_load_lds_dwordx4 v160, s[66:67]
	s_add_u32 m0, s65, 0x1000
	s_nop 0
	global_load_lds_dwordx4 v161, s[66:67]
	s_add_u32 m0, s65, 0x2000
	s_nop 0
	global_load_lds_dwordx4 v160, s[12:13]
	s_add_u32 m0, s65, 0x3000
	s_nop 0
	global_load_lds_dwordx4 v161, s[12:13]
	s_add_u32 m0, s65, 0x4000
	s_nop 0
	global_load_lds_dwordx4 v160, s[62:63]
	s_add_u32 m0, s65, 0x5000
	s_nop 0
	global_load_lds_dwordx4 v161, s[62:63]
	s_add_u32 s66, s66, 64
	s_addc_u32 s67, s67, 0
	s_add_u32 s12, s12, 64
	s_addc_u32 s13, s13, 0
	s_add_u32 s62, s62, 64
	s_addc_u32 s63, s63, 0
	s_add_u32 m0, s65, 0x6000
	s_nop 0
	global_load_lds_dwordx4 v160, s[66:67]
	s_add_u32 m0, s65, 0x7000
	s_nop 0
	global_load_lds_dwordx4 v161, s[66:67]
	s_add_u32 m0, s65, 0x8000
	s_nop 0
	global_load_lds_dwordx4 v160, s[12:13]
	s_add_u32 m0, s65, 0x9000
	s_nop 0
	global_load_lds_dwordx4 v161, s[12:13]
	s_add_u32 m0, s65, 0xa000
	s_nop 0
	global_load_lds_dwordx4 v160, s[62:63]
	s_add_u32 m0, s65, 0xb000
	s_nop 0
	global_load_lds_dwordx4 v161, s[62:63]
	s_add_u32 s66, s66, 64
	s_addc_u32 s67, s67, 0
	s_add_u32 s12, s12, 64
	s_addc_u32 s13, s13, 0
	s_add_u32 s62, s62, 64
	s_addc_u32 s63, s63, 0
	v_mov_b32_e32 v2, 0
	v_mov_b32_e32 v3, 0
	v_mov_b32_e32 v4, 0
	v_mov_b32_e32 v5, 0
	v_mov_b32_e32 v6, 0
	v_mov_b32_e32 v7, 0
	v_mov_b32_e32 v8, 0
	v_mov_b32_e32 v9, 0
	v_mov_b32_e32 v10, 0
	v_mov_b32_e32 v11, 0
	v_mov_b32_e32 v12, 0
	v_mov_b32_e32 v13, 0
	v_mov_b32_e32 v14, 0
	v_mov_b32_e32 v15, 0
	v_mov_b32_e32 v16, 0
	v_mov_b32_e32 v17, 0
	v_mov_b32_e32 v18, 0
	v_mov_b32_e32 v19, 0
	v_mov_b32_e32 v20, 0
	v_mov_b32_e32 v21, 0
	v_mov_b32_e32 v22, 0
	v_mov_b32_e32 v23, 0
	v_mov_b32_e32 v24, 0
	v_mov_b32_e32 v25, 0
	v_mov_b32_e32 v26, 0
	v_mov_b32_e32 v27, 0
	v_mov_b32_e32 v28, 0
	v_mov_b32_e32 v29, 0
	v_mov_b32_e32 v30, 0
	v_mov_b32_e32 v31, 0
	v_mov_b32_e32 v32, 0
	v_mov_b32_e32 v33, 0
	v_mov_b32_e32 v34, 0
	v_mov_b32_e32 v35, 0
	v_mov_b32_e32 v36, 0
	v_mov_b32_e32 v37, 0
	v_mov_b32_e32 v38, 0
	v_mov_b32_e32 v39, 0
	v_mov_b32_e32 v40, 0
	v_mov_b32_e32 v41, 0
	v_mov_b32_e32 v42, 0
	v_mov_b32_e32 v43, 0
	v_mov_b32_e32 v44, 0
	v_mov_b32_e32 v45, 0
	v_mov_b32_e32 v46, 0
	v_mov_b32_e32 v47, 0
	v_mov_b32_e32 v48, 0
	v_mov_b32_e32 v49, 0
	v_mov_b32_e32 v50, 0
	v_mov_b32_e32 v51, 0
	v_mov_b32_e32 v52, 0
	v_mov_b32_e32 v53, 0
	v_mov_b32_e32 v54, 0
	v_mov_b32_e32 v55, 0
	v_mov_b32_e32 v56, 0
	v_mov_b32_e32 v57, 0
	v_mov_b32_e32 v58, 0
	v_mov_b32_e32 v59, 0
	v_mov_b32_e32 v60, 0
	v_mov_b32_e32 v61, 0
	v_mov_b32_e32 v62, 0
	v_mov_b32_e32 v63, 0
	v_mov_b32_e32 v64, 0
	v_mov_b32_e32 v65, 0
	v_mov_b32_e32 v66, 0
	v_mov_b32_e32 v67, 0
	v_mov_b32_e32 v68, 0
	v_mov_b32_e32 v69, 0
	v_mov_b32_e32 v70, 0
	v_mov_b32_e32 v71, 0
	v_mov_b32_e32 v72, 0
	v_mov_b32_e32 v73, 0
	v_mov_b32_e32 v74, 0
	v_mov_b32_e32 v75, 0
	v_mov_b32_e32 v76, 0
	v_mov_b32_e32 v77, 0
	v_mov_b32_e32 v78, 0
	v_mov_b32_e32 v79, 0
	v_mov_b32_e32 v80, 0
	v_mov_b32_e32 v81, 0
	v_mov_b32_e32 v82, 0
	v_mov_b32_e32 v83, 0
	v_mov_b32_e32 v84, 0
	v_mov_b32_e32 v85, 0
	v_mov_b32_e32 v86, 0
	v_mov_b32_e32 v87, 0
	v_mov_b32_e32 v88, 0
	v_mov_b32_e32 v89, 0
	v_mov_b32_e32 v90, 0
	v_mov_b32_e32 v91, 0
	v_mov_b32_e32 v92, 0
	v_mov_b32_e32 v93, 0
	v_mov_b32_e32 v94, 0
	v_mov_b32_e32 v95, 0
	v_mov_b32_e32 v96, 0
	v_mov_b32_e32 v97, 0
	v_mov_b32_e32 v98, 0
	v_mov_b32_e32 v99, 0
	v_mov_b32_e32 v100, 0
	v_mov_b32_e32 v101, 0
	v_mov_b32_e32 v102, 0
	v_mov_b32_e32 v103, 0
	v_mov_b32_e32 v104, 0
	v_mov_b32_e32 v105, 0
	v_mov_b32_e32 v106, 0
	v_mov_b32_e32 v107, 0
	v_mov_b32_e32 v108, 0
	v_mov_b32_e32 v109, 0
	v_mov_b32_e32 v110, 0
	v_mov_b32_e32 v111, 0
	v_mov_b32_e32 v112, 0
	v_mov_b32_e32 v113, 0
	v_mov_b32_e32 v114, 0
	v_mov_b32_e32 v115, 0
	v_mov_b32_e32 v116, 0
	v_mov_b32_e32 v117, 0
	v_mov_b32_e32 v118, 0
	v_mov_b32_e32 v119, 0
	v_mov_b32_e32 v120, 0
	v_mov_b32_e32 v121, 0
	v_mov_b32_e32 v122, 0
	v_mov_b32_e32 v123, 0
	v_mov_b32_e32 v124, 0
	v_mov_b32_e32 v125, 0
	v_mov_b32_e32 v126, 0
	v_mov_b32_e32 v127, 0
	v_mov_b32_e32 v128, 0
	v_mov_b32_e32 v129, 0
	s_mov_b32 s59, 10
.Lhw_ffnup_d_loop:
	s_waitcnt vmcnt(6)
	s_barrier
	ds_read_b128 v[130:133], v154 offset:16
	ds_read_b128 v[138:141], v156 offset:8208
	ds_read_b128 v[142:145], v156 offset:10256
	ds_read_b128 v[134:137], v154 offset:2064
	ds_read_b128 v[146:149], v158 offset:8208
	ds_read_b128 v[150:153], v158 offset:10256
	s_waitcnt lgkmcnt(4)
	v_mfma_f32_32x32x16_bf16 v[2:17], v[130:133], v[138:141], v[2:17]
	ds_read_b128 v[212:215], v155 offset:16
	s_add_u32 m0, s65, 0xc000
	s_waitcnt lgkmcnt(4)
	v_mfma_f32_32x32x16_bf16 v[18:33], v[130:133], v[142:145], v[18:33]
	ds_read_b128 v[220:223], v157 offset:8208
	global_load_lds_dwordx4 v160, s[66:67]
	s_waitcnt lgkmcnt(4)
	v_mfma_f32_32x32x16_bf16 v[34:49], v[134:137], v[138:141], v[34:49]
	ds_read_b128 v[224:227], v157 offset:10256
	s_add_u32 m0, s65, 0xd000
	s_waitcnt lgkmcnt(5)
	v_mfma_f32_32x32x16_bf16 v[50:65], v[134:137], v[142:145], v[50:65]
	ds_read_b128 v[216:219], v155 offset:2064
	global_load_lds_dwordx4 v161, s[66:67]
	s_waitcnt lgkmcnt(5)
	v_mfma_f32_32x32x16_bf16 v[66:81], v[130:133], v[146:149], v[66:81]
	ds_read_b128 v[228:231], v159 offset:8208
	s_add_u32 m0, s65, 0xe000
	s_waitcnt lgkmcnt(5)
	v_mfma_f32_32x32x16_bf16 v[82:97], v[130:133], v[150:153], v[82:97]
	ds_read_b128 v[232:235], v159 offset:10256
	global_load_lds_dwordx4 v160, s[12:13]
	s_waitcnt lgkmcnt(7)
	v_mfma_f32_32x32x16_bf16 v[98:113], v[134:137], v[146:149], v[98:113]
	s_add_u32 m0, s65, 0xf000
	s_waitcnt lgkmcnt(6)
	v_mfma_f32_32x32x16_bf16 v[114:129], v[134:137], v[150:153], v[114:129]
	global_load_lds_dwordx4 v161, s[12:13]
	s_waitcnt lgkmcnt(4)
	v_mfma_f32_32x32x16_bf16 v[2:17], v[212:215], v[220:223], v[2:17]
	s_add_u32 m0, s65, 0x10000
	s_waitcnt lgkmcnt(3)
	v_mfma_f32_32x32x16_bf16 v[18:33], v[212:215], v[224:227], v[18:33]
	global_load_lds_dwordx4 v160, s[62:63]
	s_waitcnt lgkmcnt(2)
	v_mfma_f32_32x32x16_bf16 v[34:49], v[216:219], v[220:223], v[34:49]
	s_add_u32 m0, s65, 0x11000
	s_waitcnt lgkmcnt(2)
	v_mfma_f32_32x32x16_bf16 v[50:65], v[216:219], v[224:227], v[50:65]
	global_load_lds_dwordx4 v161, s[62:63]
	s_waitcnt lgkmcnt(1)
	v_mfma_f32_32x32x16_bf16 v[66:81], v[212:215], v[228:231], v[66:81]
	s_add_u32 s66, s66, 64
	s_addc_u32 s67, s67, 0
	s_waitcnt lgkmcnt(0)
	v_mfma_f32_32x32x16_bf16 v[82:97], v[212:215], v[232:235], v[82:97]
	s_add_u32 s12, s12, 64
	s_addc_u32 s13, s13, 0
	s_waitcnt lgkmcnt(1)
	v_mfma_f32_32x32x16_bf16 v[98:113], v[216:219], v[228:231], v[98:113]
	s_add_u32 s62, s62, 64
	s_addc_u32 s63, s63, 0
	s_waitcnt lgkmcnt(0)
	v_mfma_f32_32x32x16_bf16 v[114:129], v[216:219], v[232:235], v[114:129]
	s_waitcnt vmcnt(6)
	s_barrier
	ds_read_b128 v[130:133], v154 offset:24592
	ds_read_b128 v[138:141], v156 offset:32784
	ds_read_b128 v[142:145], v156 offset:34832
	ds_read_b128 v[134:137], v154 offset:26640
	ds_read_b128 v[146:149], v158 offset:32784
	ds_read_b128 v[150:153], v158 offset:34832
	s_waitcnt lgkmcnt(4)
	v_mfma_f32_32x32x16_bf16 v[2:17], v[130:133], v[138:141], v[2:17]
	ds_read_b128 v[212:215], v155 offset:24592
	s_add_u32 m0, s65, 0x0
	s_waitcnt lgkmcnt(4)
	v_mfma_f32_32x32x16_bf16 v[18:33], v[130:133], v[142:145], v[18:33]
	ds_read_b128 v[220:223], v157 offset:32784
	global_load_lds_dwordx4 v160, s[66:67]
	s_waitcnt lgkmcnt(4)
	v_mfma_f32_32x32x16_bf16 v[34:49], v[134:137], v[138:141], v[34:49]
	ds_read_b128 v[224:227], v157 offset:34832
	s_add_u32 m0, s65, 0x1000
	s_waitcnt lgkmcnt(5)
	v_mfma_f32_32x32x16_bf16 v[50:65], v[134:137], v[142:145], v[50:65]
	ds_read_b128 v[216:219], v155 offset:26640
	global_load_lds_dwordx4 v161, s[66:67]
	s_waitcnt lgkmcnt(5)
	v_mfma_f32_32x32x16_bf16 v[66:81], v[130:133], v[146:149], v[66:81]
	ds_read_b128 v[228:231], v159 offset:32784
	s_add_u32 m0, s65, 0x2000
	s_waitcnt lgkmcnt(5)
	v_mfma_f32_32x32x16_bf16 v[82:97], v[130:133], v[150:153], v[82:97]
	ds_read_b128 v[232:235], v159 offset:34832
	global_load_lds_dwordx4 v160, s[12:13]
	s_waitcnt lgkmcnt(7)
	v_mfma_f32_32x32x16_bf16 v[98:113], v[134:137], v[146:149], v[98:113]
	s_add_u32 m0, s65, 0x3000
	s_waitcnt lgkmcnt(6)
	v_mfma_f32_32x32x16_bf16 v[114:129], v[134:137], v[150:153], v[114:129]
	global_load_lds_dwordx4 v161, s[12:13]
	s_waitcnt lgkmcnt(4)
	v_mfma_f32_32x32x16_bf16 v[2:17], v[212:215], v[220:223], v[2:17]
	s_add_u32 m0, s65, 0x4000
	s_waitcnt lgkmcnt(3)
	v_mfma_f32_32x32x16_bf16 v[18:33], v[212:215], v[224:227], v[18:33]
	global_load_lds_dwordx4 v160, s[62:63]
	s_waitcnt lgkmcnt(2)
	v_mfma_f32_32x32x16_bf16 v[34:49], v[216:219], v[220:223], v[34:49]
	s_add_u32 m0, s65, 0x5000
	s_waitcnt lgkmcnt(2)
	v_mfma_f32_32x32x16_bf16 v[50:65], v[216:219], v[224:227], v[50:65]
	global_load_lds_dwordx4 v161, s[62:63]
	s_waitcnt lgkmcnt(1)
	v_mfma_f32_32x32x16_bf16 v[66:81], v[212:215], v[228:231], v[66:81]
	s_add_u32 s66, s66, 64
	s_addc_u32 s67, s67, 0
	s_waitcnt lgkmcnt(0)
	v_mfma_f32_32x32x16_bf16 v[82:97], v[212:215], v[232:235], v[82:97]
	s_add_u32 s12, s12, 64
	s_addc_u32 s13, s13, 0
	s_waitcnt lgkmcnt(1)
	v_mfma_f32_32x32x16_bf16 v[98:113], v[216:219], v[228:231], v[98:113]
	s_add_u32 s62, s62, 64
	s_addc_u32 s63, s63, 0
	s_waitcnt lgkmcnt(0)
	v_mfma_f32_32x32x16_bf16 v[114:129], v[216:219], v[232:235], v[114:129]
	s_waitcnt vmcnt(6)
	s_barrier
	ds_read_b128 v[130:133], v154 offset:49168
	ds_read_b128 v[138:141], v156 offset:57360
	ds_read_b128 v[142:145], v156 offset:59408
	ds_read_b128 v[134:137], v154 offset:51216
	ds_read_b128 v[146:149], v158 offset:57360
	ds_read_b128 v[150:153], v158 offset:59408
	s_waitcnt lgkmcnt(4)
	v_mfma_f32_32x32x16_bf16 v[2:17], v[130:133], v[138:141], v[2:17]
	ds_read_b128 v[212:215], v155 offset:49168
	s_add_u32 m0, s65, 0x6000
	s_waitcnt lgkmcnt(4)
	v_mfma_f32_32x32x16_bf16 v[18:33], v[130:133], v[142:145], v[18:33]
	ds_read_b128 v[220:223], v157 offset:57360
	global_load_lds_dwordx4 v160, s[66:67]
	s_waitcnt lgkmcnt(4)
	v_mfma_f32_32x32x16_bf16 v[34:49], v[134:137], v[138:141], v[34:49]
	ds_read_b128 v[224:227], v157 offset:59408
	s_add_u32 m0, s65, 0x7000
	s_waitcnt lgkmcnt(5)
	v_mfma_f32_32x32x16_bf16 v[50:65], v[134:137], v[142:145], v[50:65]
	ds_read_b128 v[216:219], v155 offset:51216
	global_load_lds_dwordx4 v161, s[66:67]
	s_waitcnt lgkmcnt(5)
	v_mfma_f32_32x32x16_bf16 v[66:81], v[130:133], v[146:149], v[66:81]
	ds_read_b128 v[228:231], v159 offset:57360
	s_add_u32 m0, s65, 0x8000
	s_waitcnt lgkmcnt(5)
	v_mfma_f32_32x32x16_bf16 v[82:97], v[130:133], v[150:153], v[82:97]
	ds_read_b128 v[232:235], v159 offset:59408
	global_load_lds_dwordx4 v160, s[12:13]
	s_waitcnt lgkmcnt(7)
	v_mfma_f32_32x32x16_bf16 v[98:113], v[134:137], v[146:149], v[98:113]
	s_add_u32 m0, s65, 0x9000
	s_waitcnt lgkmcnt(6)
	v_mfma_f32_32x32x16_bf16 v[114:129], v[134:137], v[150:153], v[114:129]
	global_load_lds_dwordx4 v161, s[12:13]
	s_waitcnt lgkmcnt(4)
	v_mfma_f32_32x32x16_bf16 v[2:17], v[212:215], v[220:223], v[2:17]
	s_add_u32 m0, s65, 0xa000
	s_waitcnt lgkmcnt(3)
	v_mfma_f32_32x32x16_bf16 v[18:33], v[212:215], v[224:227], v[18:33]
	global_load_lds_dwordx4 v160, s[62:63]
	s_waitcnt lgkmcnt(2)
	v_mfma_f32_32x32x16_bf16 v[34:49], v[216:219], v[220:223], v[34:49]
	s_add_u32 m0, s65, 0xb000
	s_waitcnt lgkmcnt(2)
	v_mfma_f32_32x32x16_bf16 v[50:65], v[216:219], v[224:227], v[50:65]
	global_load_lds_dwordx4 v161, s[62:63]
	s_waitcnt lgkmcnt(1)
	v_mfma_f32_32x32x16_bf16 v[66:81], v[212:215], v[228:231], v[66:81]
	s_add_u32 s66, s66, 64
	s_addc_u32 s67, s67, 0
	s_waitcnt lgkmcnt(0)
	v_mfma_f32_32x32x16_bf16 v[82:97], v[212:215], v[232:235], v[82:97]
	s_add_u32 s12, s12, 64
	s_addc_u32 s13, s13, 0
	s_waitcnt lgkmcnt(1)
	v_mfma_f32_32x32x16_bf16 v[98:113], v[216:219], v[228:231], v[98:113]
	s_add_u32 s62, s62, 64
	s_addc_u32 s63, s63, 0
	s_waitcnt lgkmcnt(0)
	v_mfma_f32_32x32x16_bf16 v[114:129], v[216:219], v[232:235], v[114:129]
	s_sub_u32 s59, s59, 1
	s_cmp_lg_u32 s59, 0
	s_cbranch_scc1 .Lhw_ffnup_d_loop
	s_waitcnt vmcnt(6)
	s_barrier
	ds_read_b128 v[130:133], v154 offset:16
	ds_read_b128 v[138:141], v156 offset:8208
	ds_read_b128 v[142:145], v156 offset:10256
	ds_read_b128 v[134:137], v154 offset:2064
	ds_read_b128 v[146:149], v158 offset:8208
	ds_read_b128 v[150:153], v158 offset:10256
	s_waitcnt lgkmcnt(4)
	v_mfma_f32_32x32x16_bf16 v[2:17], v[130:133], v[138:141], v[2:17]
	ds_read_b128 v[212:215], v155 offset:16
	s_waitcnt lgkmcnt(4)
	v_mfma_f32_32x32x16_bf16 v[18:33], v[130:133], v[142:145], v[18:33]
	ds_read_b128 v[220:223], v157 offset:8208
	s_waitcnt lgkmcnt(4)
	v_mfma_f32_32x32x16_bf16 v[34:49], v[134:137], v[138:141], v[34:49]
	ds_read_b128 v[224:227], v157 offset:10256
	s_waitcnt lgkmcnt(5)
	v_mfma_f32_32x32x16_bf16 v[50:65], v[134:137], v[142:145], v[50:65]
	ds_read_b128 v[216:219], v155 offset:2064
	s_waitcnt lgkmcnt(5)
	v_mfma_f32_32x32x16_bf16 v[66:81], v[130:133], v[146:149], v[66:81]
	ds_read_b128 v[228:231], v159 offset:8208
	s_waitcnt lgkmcnt(5)
	v_mfma_f32_32x32x16_bf16 v[82:97], v[130:133], v[150:153], v[82:97]
	ds_read_b128 v[232:235], v159 offset:10256
	s_waitcnt lgkmcnt(7)
	v_mfma_f32_32x32x16_bf16 v[98:113], v[134:137], v[146:149], v[98:113]
	s_waitcnt lgkmcnt(6)
	v_mfma_f32_32x32x16_bf16 v[114:129], v[134:137], v[150:153], v[114:129]
	s_waitcnt lgkmcnt(4)
	v_mfma_f32_32x32x16_bf16 v[2:17], v[212:215], v[220:223], v[2:17]
	s_waitcnt lgkmcnt(3)
	v_mfma_f32_32x32x16_bf16 v[18:33], v[212:215], v[224:227], v[18:33]
	s_waitcnt lgkmcnt(2)
	v_mfma_f32_32x32x16_bf16 v[34:49], v[216:219], v[220:223], v[34:49]
	s_waitcnt lgkmcnt(2)
	v_mfma_f32_32x32x16_bf16 v[50:65], v[216:219], v[224:227], v[50:65]
	s_waitcnt lgkmcnt(1)
	v_mfma_f32_32x32x16_bf16 v[66:81], v[212:215], v[228:231], v[66:81]
	s_waitcnt lgkmcnt(0)
	v_mfma_f32_32x32x16_bf16 v[82:97], v[212:215], v[232:235], v[82:97]
	s_waitcnt lgkmcnt(1)
	v_mfma_f32_32x32x16_bf16 v[98:113], v[216:219], v[228:231], v[98:113]
	s_waitcnt lgkmcnt(0)
	v_mfma_f32_32x32x16_bf16 v[114:129], v[216:219], v[232:235], v[114:129]
	s_waitcnt vmcnt(0)
	s_barrier
	ds_read_b128 v[130:133], v154 offset:24592
	ds_read_b128 v[138:141], v156 offset:32784
	ds_read_b128 v[142:145], v156 offset:34832
	ds_read_b128 v[134:137], v154 offset:26640
	ds_read_b128 v[146:149], v158 offset:32784
	ds_read_b128 v[150:153], v158 offset:34832
	s_waitcnt lgkmcnt(4)
	v_mfma_f32_32x32x16_bf16 v[2:17], v[130:133], v[138:141], v[2:17]
	ds_read_b128 v[212:215], v155 offset:24592
	s_waitcnt lgkmcnt(4)
	v_mfma_f32_32x32x16_bf16 v[18:33], v[130:133], v[142:145], v[18:33]
	ds_read_b128 v[220:223], v157 offset:32784
	s_waitcnt lgkmcnt(4)
	v_mfma_f32_32x32x16_bf16 v[34:49], v[134:137], v[138:141], v[34:49]
	ds_read_b128 v[224:227], v157 offset:34832
	s_waitcnt lgkmcnt(5)
	v_mfma_f32_32x32x16_bf16 v[50:65], v[134:137], v[142:145], v[50:65]
	ds_read_b128 v[216:219], v155 offset:26640
	s_waitcnt lgkmcnt(5)
	v_mfma_f32_32x32x16_bf16 v[66:81], v[130:133], v[146:149], v[66:81]
	ds_read_b128 v[228:231], v159 offset:32784
	s_waitcnt lgkmcnt(5)
	v_mfma_f32_32x32x16_bf16 v[82:97], v[130:133], v[150:153], v[82:97]
	ds_read_b128 v[232:235], v159 offset:34832
	s_waitcnt lgkmcnt(7)
	v_mfma_f32_32x32x16_bf16 v[98:113], v[134:137], v[146:149], v[98:113]
	s_waitcnt lgkmcnt(6)
	v_mfma_f32_32x32x16_bf16 v[114:129], v[134:137], v[150:153], v[114:129]
	s_waitcnt lgkmcnt(4)
	v_mfma_f32_32x32x16_bf16 v[2:17], v[212:215], v[220:223], v[2:17]
	s_waitcnt lgkmcnt(3)
	v_mfma_f32_32x32x16_bf16 v[18:33], v[212:215], v[224:227], v[18:33]
	s_waitcnt lgkmcnt(2)
	v_mfma_f32_32x32x16_bf16 v[34:49], v[216:219], v[220:223], v[34:49]
	s_waitcnt lgkmcnt(2)
	v_mfma_f32_32x32x16_bf16 v[50:65], v[216:219], v[224:227], v[50:65]
	s_waitcnt lgkmcnt(1)
	v_mfma_f32_32x32x16_bf16 v[66:81], v[212:215], v[228:231], v[66:81]
	s_waitcnt lgkmcnt(0)
	v_mfma_f32_32x32x16_bf16 v[82:97], v[212:215], v[232:235], v[82:97]
	s_waitcnt lgkmcnt(1)
	v_mfma_f32_32x32x16_bf16 v[98:113], v[216:219], v[228:231], v[98:113]
	s_waitcnt lgkmcnt(0)
	v_mfma_f32_32x32x16_bf16 v[114:129], v[216:219], v[232:235], v[114:129]
	s_nop 7
	s_nop 7
	s_mul_i32 vcc_lo, s6, 0x1600
	s_add_u32 s66, s8, vcc_lo
	s_addc_u32 s67, s9, 0
	s_add_u32 s66, s66, s14
	s_addc_u32 s67, s67, 0
	v_mul_f32_e32 v171, 0xbfb8aa3b, v2
	v_mul_f32_e32 v172, 0xbfb8aa3b, v3
	v_mul_f32_e32 v173, 0xbfb8aa3b, v4
	v_mul_f32_e32 v174, 0xbfb8aa3b, v5
	v_exp_f32_e32 v171, v171
	v_exp_f32_e32 v172, v172
	v_exp_f32_e32 v173, v173
	v_exp_f32_e32 v174, v174
	s_nop 0
	v_add_f32_e32 v171, 1.0, v171
	v_add_f32_e32 v172, 1.0, v172
	v_add_f32_e32 v173, 1.0, v173
	v_add_f32_e32 v174, 1.0, v174
	v_rcp_f32_e32 v171, v171
	v_rcp_f32_e32 v172, v172
	v_rcp_f32_e32 v173, v173
	v_rcp_f32_e32 v174, v174
	s_nop 0
	v_mul_f32_e32 v171, v2, v171
	v_mul_f32_e32 v172, v3, v172
	v_mul_f32_e32 v173, v4, v173
	v_mul_f32_e32 v174, v5, v174
	v_mul_f32_e32 v171, v18, v171
	v_mul_f32_e32 v172, v19, v172
	v_mul_f32_e32 v173, v20, v173
	v_mul_f32_e32 v174, v21, v174
	v_cvt_pk_bf16_f32 v179, v171, v171
	v_cvt_pk_bf16_f32 v180, v172, v172
	v_cvt_pk_bf16_f32 v181, v173, v173
	v_cvt_pk_bf16_f32 v182, v174, v174
	global_store_short v162, v179, s[66:67]
	global_store_short v163, v180, s[66:67]
	global_store_short v164, v181, s[66:67]
	global_store_short v165, v182, s[66:67]
	s_add_u32 s66, s66, 0xb000
	s_addc_u32 s67, s67, 0
	v_mul_f32_e32 v171, 0xbfb8aa3b, v6
	v_mul_f32_e32 v172, 0xbfb8aa3b, v7
	v_mul_f32_e32 v173, 0xbfb8aa3b, v8
	v_mul_f32_e32 v174, 0xbfb8aa3b, v9
	v_exp_f32_e32 v171, v171
	v_exp_f32_e32 v172, v172
	v_exp_f32_e32 v173, v173
	v_exp_f32_e32 v174, v174
	s_nop 0
	v_add_f32_e32 v171, 1.0, v171
	v_add_f32_e32 v172, 1.0, v172
	v_add_f32_e32 v173, 1.0, v173
	v_add_f32_e32 v174, 1.0, v174
	v_rcp_f32_e32 v171, v171
	v_rcp_f32_e32 v172, v172
	v_rcp_f32_e32 v173, v173
	v_rcp_f32_e32 v174, v174
	s_nop 0
	v_mul_f32_e32 v171, v6, v171
	v_mul_f32_e32 v172, v7, v172
	v_mul_f32_e32 v173, v8, v173
	v_mul_f32_e32 v174, v9, v174
	v_mul_f32_e32 v171, v22, v171
	v_mul_f32_e32 v172, v23, v172
	v_mul_f32_e32 v173, v24, v173
	v_mul_f32_e32 v174, v25, v174
	v_cvt_pk_bf16_f32 v179, v171, v171
	v_cvt_pk_bf16_f32 v180, v172, v172
	v_cvt_pk_bf16_f32 v181, v173, v173
	v_cvt_pk_bf16_f32 v182, v174, v174
	global_store_short v162, v179, s[66:67]
	global_store_short v163, v180, s[66:67]
	global_store_short v164, v181, s[66:67]
	global_store_short v165, v182, s[66:67]
	s_add_u32 s66, s66, 0xb000
	s_addc_u32 s67, s67, 0
	v_mul_f32_e32 v171, 0xbfb8aa3b, v10
	v_mul_f32_e32 v172, 0xbfb8aa3b, v11
	v_mul_f32_e32 v173, 0xbfb8aa3b, v12
	v_mul_f32_e32 v174, 0xbfb8aa3b, v13
	v_exp_f32_e32 v171, v171
	v_exp_f32_e32 v172, v172
	v_exp_f32_e32 v173, v173
	v_exp_f32_e32 v174, v174
	s_nop 0
	v_add_f32_e32 v171, 1.0, v171
	v_add_f32_e32 v172, 1.0, v172
	v_add_f32_e32 v173, 1.0, v173
	v_add_f32_e32 v174, 1.0, v174
	v_rcp_f32_e32 v171, v171
	v_rcp_f32_e32 v172, v172
	v_rcp_f32_e32 v173, v173
	v_rcp_f32_e32 v174, v174
	s_nop 0
	v_mul_f32_e32 v171, v10, v171
	v_mul_f32_e32 v172, v11, v172
	v_mul_f32_e32 v173, v12, v173
	v_mul_f32_e32 v174, v13, v174
	v_mul_f32_e32 v171, v26, v171
	v_mul_f32_e32 v172, v27, v172
	v_mul_f32_e32 v173, v28, v173
	v_mul_f32_e32 v174, v29, v174
	v_cvt_pk_bf16_f32 v179, v171, v171
	v_cvt_pk_bf16_f32 v180, v172, v172
	v_cvt_pk_bf16_f32 v181, v173, v173
	v_cvt_pk_bf16_f32 v182, v174, v174
	global_store_short v162, v179, s[66:67]
	global_store_short v163, v180, s[66:67]
	global_store_short v164, v181, s[66:67]
	global_store_short v165, v182, s[66:67]
	s_add_u32 s66, s66, 0xb000
	s_addc_u32 s67, s67, 0
	v_mul_f32_e32 v171, 0xbfb8aa3b, v14
	v_mul_f32_e32 v172, 0xbfb8aa3b, v15
	v_mul_f32_e32 v173, 0xbfb8aa3b, v16
	v_mul_f32_e32 v174, 0xbfb8aa3b, v17
	v_exp_f32_e32 v171, v171
	v_exp_f32_e32 v172, v172
	v_exp_f32_e32 v173, v173
	v_exp_f32_e32 v174, v174
	s_nop 0
	v_add_f32_e32 v171, 1.0, v171
	v_add_f32_e32 v172, 1.0, v172
	v_add_f32_e32 v173, 1.0, v173
	v_add_f32_e32 v174, 1.0, v174
	v_rcp_f32_e32 v171, v171
	v_rcp_f32_e32 v172, v172
	v_rcp_f32_e32 v173, v173
	v_rcp_f32_e32 v174, v174
	s_nop 0
	v_mul_f32_e32 v171, v14, v171
	v_mul_f32_e32 v172, v15, v172
	v_mul_f32_e32 v173, v16, v173
	v_mul_f32_e32 v174, v17, v174
	v_mul_f32_e32 v171, v30, v171
	v_mul_f32_e32 v172, v31, v172
	v_mul_f32_e32 v173, v32, v173
	v_mul_f32_e32 v174, v33, v174
	v_cvt_pk_bf16_f32 v179, v171, v171
	v_cvt_pk_bf16_f32 v180, v172, v172
	v_cvt_pk_bf16_f32 v181, v173, v173
	v_cvt_pk_bf16_f32 v182, v174, v174
	global_store_short v162, v179, s[66:67]
	global_store_short v163, v180, s[66:67]
	global_store_short v164, v181, s[66:67]
	global_store_short v165, v182, s[66:67]
	s_add_u32 s66, s66, 0xb000
	s_addc_u32 s67, s67, 0
	v_mul_f32_e32 v171, 0xbfb8aa3b, v34
	v_mul_f32_e32 v172, 0xbfb8aa3b, v35
	v_mul_f32_e32 v173, 0xbfb8aa3b, v36
	v_mul_f32_e32 v174, 0xbfb8aa3b, v37
	v_exp_f32_e32 v171, v171
	v_exp_f32_e32 v172, v172
	v_exp_f32_e32 v173, v173
	v_exp_f32_e32 v174, v174
	s_nop 0
	v_add_f32_e32 v171, 1.0, v171
	v_add_f32_e32 v172, 1.0, v172
	v_add_f32_e32 v173, 1.0, v173
	v_add_f32_e32 v174, 1.0, v174
	v_rcp_f32_e32 v171, v171
	v_rcp_f32_e32 v172, v172
	v_rcp_f32_e32 v173, v173
	v_rcp_f32_e32 v174, v174
	s_nop 0
	v_mul_f32_e32 v171, v34, v171
	v_mul_f32_e32 v172, v35, v172
	v_mul_f32_e32 v173, v36, v173
	v_mul_f32_e32 v174, v37, v174
	v_mul_f32_e32 v171, v50, v171
	v_mul_f32_e32 v172, v51, v172
	v_mul_f32_e32 v173, v52, v173
	v_mul_f32_e32 v174, v53, v174
	v_cvt_pk_bf16_f32 v179, v171, v171
	v_cvt_pk_bf16_f32 v180, v172, v172
	v_cvt_pk_bf16_f32 v181, v173, v173
	v_cvt_pk_bf16_f32 v182, v174, v174
	global_store_short v162, v179, s[66:67]
	global_store_short v163, v180, s[66:67]
	global_store_short v164, v181, s[66:67]
	global_store_short v165, v182, s[66:67]
	s_add_u32 s66, s66, 0xb000
	s_addc_u32 s67, s67, 0
	v_mul_f32_e32 v171, 0xbfb8aa3b, v38
	v_mul_f32_e32 v172, 0xbfb8aa3b, v39
	v_mul_f32_e32 v173, 0xbfb8aa3b, v40
	v_mul_f32_e32 v174, 0xbfb8aa3b, v41
	v_exp_f32_e32 v171, v171
	v_exp_f32_e32 v172, v172
	v_exp_f32_e32 v173, v173
	v_exp_f32_e32 v174, v174
	s_nop 0
	v_add_f32_e32 v171, 1.0, v171
	v_add_f32_e32 v172, 1.0, v172
	v_add_f32_e32 v173, 1.0, v173
	v_add_f32_e32 v174, 1.0, v174
	v_rcp_f32_e32 v171, v171
	v_rcp_f32_e32 v172, v172
	v_rcp_f32_e32 v173, v173
	v_rcp_f32_e32 v174, v174
	s_nop 0
	v_mul_f32_e32 v171, v38, v171
	v_mul_f32_e32 v172, v39, v172
	v_mul_f32_e32 v173, v40, v173
	v_mul_f32_e32 v174, v41, v174
	v_mul_f32_e32 v171, v54, v171
	v_mul_f32_e32 v172, v55, v172
	v_mul_f32_e32 v173, v56, v173
	v_mul_f32_e32 v174, v57, v174
	v_cvt_pk_bf16_f32 v179, v171, v171
	v_cvt_pk_bf16_f32 v180, v172, v172
	v_cvt_pk_bf16_f32 v181, v173, v173
	v_cvt_pk_bf16_f32 v182, v174, v174
	global_store_short v162, v179, s[66:67]
	global_store_short v163, v180, s[66:67]
	global_store_short v164, v181, s[66:67]
	global_store_short v165, v182, s[66:67]
	s_add_u32 s66, s66, 0xb000
	s_addc_u32 s67, s67, 0
	v_mul_f32_e32 v171, 0xbfb8aa3b, v42
	v_mul_f32_e32 v172, 0xbfb8aa3b, v43
	v_mul_f32_e32 v173, 0xbfb8aa3b, v44
	v_mul_f32_e32 v174, 0xbfb8aa3b, v45
	v_exp_f32_e32 v171, v171
	v_exp_f32_e32 v172, v172
	v_exp_f32_e32 v173, v173
	v_exp_f32_e32 v174, v174
	s_nop 0
	v_add_f32_e32 v171, 1.0, v171
	v_add_f32_e32 v172, 1.0, v172
	v_add_f32_e32 v173, 1.0, v173
	v_add_f32_e32 v174, 1.0, v174
	v_rcp_f32_e32 v171, v171
	v_rcp_f32_e32 v172, v172
	v_rcp_f32_e32 v173, v173
	v_rcp_f32_e32 v174, v174
	s_nop 0
	v_mul_f32_e32 v171, v42, v171
	v_mul_f32_e32 v172, v43, v172
	v_mul_f32_e32 v173, v44, v173
	v_mul_f32_e32 v174, v45, v174
	v_mul_f32_e32 v171, v58, v171
	v_mul_f32_e32 v172, v59, v172
	v_mul_f32_e32 v173, v60, v173
	v_mul_f32_e32 v174, v61, v174
	v_cvt_pk_bf16_f32 v179, v171, v171
	v_cvt_pk_bf16_f32 v180, v172, v172
	v_cvt_pk_bf16_f32 v181, v173, v173
	v_cvt_pk_bf16_f32 v182, v174, v174
	global_store_short v162, v179, s[66:67]
	global_store_short v163, v180, s[66:67]
	global_store_short v164, v181, s[66:67]
	global_store_short v165, v182, s[66:67]
	s_add_u32 s66, s66, 0xb000
	s_addc_u32 s67, s67, 0
	v_mul_f32_e32 v171, 0xbfb8aa3b, v46
	v_mul_f32_e32 v172, 0xbfb8aa3b, v47
	v_mul_f32_e32 v173, 0xbfb8aa3b, v48
	v_mul_f32_e32 v174, 0xbfb8aa3b, v49
	v_exp_f32_e32 v171, v171
	v_exp_f32_e32 v172, v172
	v_exp_f32_e32 v173, v173
	v_exp_f32_e32 v174, v174
	s_nop 0
	v_add_f32_e32 v171, 1.0, v171
	v_add_f32_e32 v172, 1.0, v172
	v_add_f32_e32 v173, 1.0, v173
	v_add_f32_e32 v174, 1.0, v174
	v_rcp_f32_e32 v171, v171
	v_rcp_f32_e32 v172, v172
	v_rcp_f32_e32 v173, v173
	v_rcp_f32_e32 v174, v174
	s_nop 0
	v_mul_f32_e32 v171, v46, v171
	v_mul_f32_e32 v172, v47, v172
	v_mul_f32_e32 v173, v48, v173
	v_mul_f32_e32 v174, v49, v174
	v_mul_f32_e32 v171, v62, v171
	v_mul_f32_e32 v172, v63, v172
	v_mul_f32_e32 v173, v64, v173
	v_mul_f32_e32 v174, v65, v174
	v_cvt_pk_bf16_f32 v179, v171, v171
	v_cvt_pk_bf16_f32 v180, v172, v172
	v_cvt_pk_bf16_f32 v181, v173, v173
	v_cvt_pk_bf16_f32 v182, v174, v174
	global_store_short v162, v179, s[66:67]
	global_store_short v163, v180, s[66:67]
	global_store_short v164, v181, s[66:67]
	global_store_short v165, v182, s[66:67]
	s_sub_u32 s66, s66, 0x4cf80
	s_subb_u32 s67, s67, 0
	v_mul_f32_e32 v171, 0xbfb8aa3b, v66
	v_mul_f32_e32 v172, 0xbfb8aa3b, v67
	v_mul_f32_e32 v173, 0xbfb8aa3b, v68
	v_mul_f32_e32 v174, 0xbfb8aa3b, v69
	v_exp_f32_e32 v171, v171
	v_exp_f32_e32 v172, v172
	v_exp_f32_e32 v173, v173
	v_exp_f32_e32 v174, v174
	s_nop 0
	v_add_f32_e32 v171, 1.0, v171
	v_add_f32_e32 v172, 1.0, v172
	v_add_f32_e32 v173, 1.0, v173
	v_add_f32_e32 v174, 1.0, v174
	v_rcp_f32_e32 v171, v171
	v_rcp_f32_e32 v172, v172
	v_rcp_f32_e32 v173, v173
	v_rcp_f32_e32 v174, v174
	s_nop 0
	v_mul_f32_e32 v171, v66, v171
	v_mul_f32_e32 v172, v67, v172
	v_mul_f32_e32 v173, v68, v173
	v_mul_f32_e32 v174, v69, v174
	v_mul_f32_e32 v171, v82, v171
	v_mul_f32_e32 v172, v83, v172
	v_mul_f32_e32 v173, v84, v173
	v_mul_f32_e32 v174, v85, v174
	v_cvt_pk_bf16_f32 v179, v171, v171
	v_cvt_pk_bf16_f32 v180, v172, v172
	v_cvt_pk_bf16_f32 v181, v173, v173
	v_cvt_pk_bf16_f32 v182, v174, v174
	global_store_short v162, v179, s[66:67]
	global_store_short v163, v180, s[66:67]
	global_store_short v164, v181, s[66:67]
	global_store_short v165, v182, s[66:67]
	s_add_u32 s66, s66, 0xb000
	s_addc_u32 s67, s67, 0
	v_mul_f32_e32 v171, 0xbfb8aa3b, v70
	v_mul_f32_e32 v172, 0xbfb8aa3b, v71
	v_mul_f32_e32 v173, 0xbfb8aa3b, v72
	v_mul_f32_e32 v174, 0xbfb8aa3b, v73
	v_exp_f32_e32 v171, v171
	v_exp_f32_e32 v172, v172
	v_exp_f32_e32 v173, v173
	v_exp_f32_e32 v174, v174
	s_nop 0
	v_add_f32_e32 v171, 1.0, v171
	v_add_f32_e32 v172, 1.0, v172
	v_add_f32_e32 v173, 1.0, v173
	v_add_f32_e32 v174, 1.0, v174
	v_rcp_f32_e32 v171, v171
	v_rcp_f32_e32 v172, v172
	v_rcp_f32_e32 v173, v173
	v_rcp_f32_e32 v174, v174
	s_nop 0
	v_mul_f32_e32 v171, v70, v171
	v_mul_f32_e32 v172, v71, v172
	v_mul_f32_e32 v173, v72, v173
	v_mul_f32_e32 v174, v73, v174
	v_mul_f32_e32 v171, v86, v171
	v_mul_f32_e32 v172, v87, v172
	v_mul_f32_e32 v173, v88, v173
	v_mul_f32_e32 v174, v89, v174
	v_cvt_pk_bf16_f32 v179, v171, v171
	v_cvt_pk_bf16_f32 v180, v172, v172
	v_cvt_pk_bf16_f32 v181, v173, v173
	v_cvt_pk_bf16_f32 v182, v174, v174
	global_store_short v162, v179, s[66:67]
	global_store_short v163, v180, s[66:67]
	global_store_short v164, v181, s[66:67]
	global_store_short v165, v182, s[66:67]
	s_add_u32 s66, s66, 0xb000
	s_addc_u32 s67, s67, 0
	v_mul_f32_e32 v171, 0xbfb8aa3b, v74
	v_mul_f32_e32 v172, 0xbfb8aa3b, v75
	v_mul_f32_e32 v173, 0xbfb8aa3b, v76
	v_mul_f32_e32 v174, 0xbfb8aa3b, v77
	v_exp_f32_e32 v171, v171
	v_exp_f32_e32 v172, v172
	v_exp_f32_e32 v173, v173
	v_exp_f32_e32 v174, v174
	s_nop 0
	v_add_f32_e32 v171, 1.0, v171
	v_add_f32_e32 v172, 1.0, v172
	v_add_f32_e32 v173, 1.0, v173
	v_add_f32_e32 v174, 1.0, v174
	v_rcp_f32_e32 v171, v171
	v_rcp_f32_e32 v172, v172
	v_rcp_f32_e32 v173, v173
	v_rcp_f32_e32 v174, v174
	s_nop 0
	v_mul_f32_e32 v171, v74, v171
	v_mul_f32_e32 v172, v75, v172
	v_mul_f32_e32 v173, v76, v173
	v_mul_f32_e32 v174, v77, v174
	v_mul_f32_e32 v171, v90, v171
	v_mul_f32_e32 v172, v91, v172
	v_mul_f32_e32 v173, v92, v173
	v_mul_f32_e32 v174, v93, v174
	v_cvt_pk_bf16_f32 v179, v171, v171
	v_cvt_pk_bf16_f32 v180, v172, v172
	v_cvt_pk_bf16_f32 v181, v173, v173
	v_cvt_pk_bf16_f32 v182, v174, v174
	global_store_short v162, v179, s[66:67]
	global_store_short v163, v180, s[66:67]
	global_store_short v164, v181, s[66:67]
	global_store_short v165, v182, s[66:67]
	s_add_u32 s66, s66, 0xb000
	s_addc_u32 s67, s67, 0
	v_mul_f32_e32 v171, 0xbfb8aa3b, v78
	v_mul_f32_e32 v172, 0xbfb8aa3b, v79
	v_mul_f32_e32 v173, 0xbfb8aa3b, v80
	v_mul_f32_e32 v174, 0xbfb8aa3b, v81
	v_exp_f32_e32 v171, v171
	v_exp_f32_e32 v172, v172
	v_exp_f32_e32 v173, v173
	v_exp_f32_e32 v174, v174
	s_nop 0
	v_add_f32_e32 v171, 1.0, v171
	v_add_f32_e32 v172, 1.0, v172
	v_add_f32_e32 v173, 1.0, v173
	v_add_f32_e32 v174, 1.0, v174
	v_rcp_f32_e32 v171, v171
	v_rcp_f32_e32 v172, v172
	v_rcp_f32_e32 v173, v173
	v_rcp_f32_e32 v174, v174
	s_nop 0
	v_mul_f32_e32 v171, v78, v171
	v_mul_f32_e32 v172, v79, v172
	v_mul_f32_e32 v173, v80, v173
	v_mul_f32_e32 v174, v81, v174
	v_mul_f32_e32 v171, v94, v171
	v_mul_f32_e32 v172, v95, v172
	v_mul_f32_e32 v173, v96, v173
	v_mul_f32_e32 v174, v97, v174
	v_cvt_pk_bf16_f32 v179, v171, v171
	v_cvt_pk_bf16_f32 v180, v172, v172
	v_cvt_pk_bf16_f32 v181, v173, v173
	v_cvt_pk_bf16_f32 v182, v174, v174
	global_store_short v162, v179, s[66:67]
	global_store_short v163, v180, s[66:67]
	global_store_short v164, v181, s[66:67]
	global_store_short v165, v182, s[66:67]
	s_add_u32 s66, s66, 0xb000
	s_addc_u32 s67, s67, 0
	v_mul_f32_e32 v171, 0xbfb8aa3b, v98
	v_mul_f32_e32 v172, 0xbfb8aa3b, v99
	v_mul_f32_e32 v173, 0xbfb8aa3b, v100
	v_mul_f32_e32 v174, 0xbfb8aa3b, v101
	v_exp_f32_e32 v171, v171
	v_exp_f32_e32 v172, v172
	v_exp_f32_e32 v173, v173
	v_exp_f32_e32 v174, v174
	s_nop 0
	v_add_f32_e32 v171, 1.0, v171
	v_add_f32_e32 v172, 1.0, v172
	v_add_f32_e32 v173, 1.0, v173
	v_add_f32_e32 v174, 1.0, v174
	v_rcp_f32_e32 v171, v171
	v_rcp_f32_e32 v172, v172
	v_rcp_f32_e32 v173, v173
	v_rcp_f32_e32 v174, v174
	s_nop 0
	v_mul_f32_e32 v171, v98, v171
	v_mul_f32_e32 v172, v99, v172
	v_mul_f32_e32 v173, v100, v173
	v_mul_f32_e32 v174, v101, v174
	v_mul_f32_e32 v171, v114, v171
	v_mul_f32_e32 v172, v115, v172
	v_mul_f32_e32 v173, v116, v173
	v_mul_f32_e32 v174, v117, v174
	v_cvt_pk_bf16_f32 v179, v171, v171
	v_cvt_pk_bf16_f32 v180, v172, v172
	v_cvt_pk_bf16_f32 v181, v173, v173
	v_cvt_pk_bf16_f32 v182, v174, v174
	global_store_short v162, v179, s[66:67]
	global_store_short v163, v180, s[66:67]
	global_store_short v164, v181, s[66:67]
	global_store_short v165, v182, s[66:67]
	s_add_u32 s66, s66, 0xb000
	s_addc_u32 s67, s67, 0
	v_mul_f32_e32 v171, 0xbfb8aa3b, v102
	v_mul_f32_e32 v172, 0xbfb8aa3b, v103
	v_mul_f32_e32 v173, 0xbfb8aa3b, v104
	v_mul_f32_e32 v174, 0xbfb8aa3b, v105
	v_exp_f32_e32 v171, v171
	v_exp_f32_e32 v172, v172
	v_exp_f32_e32 v173, v173
	v_exp_f32_e32 v174, v174
	s_nop 0
	v_add_f32_e32 v171, 1.0, v171
	v_add_f32_e32 v172, 1.0, v172
	v_add_f32_e32 v173, 1.0, v173
	v_add_f32_e32 v174, 1.0, v174
	v_rcp_f32_e32 v171, v171
	v_rcp_f32_e32 v172, v172
	v_rcp_f32_e32 v173, v173
	v_rcp_f32_e32 v174, v174
	s_nop 0
	v_mul_f32_e32 v171, v102, v171
	v_mul_f32_e32 v172, v103, v172
	v_mul_f32_e32 v173, v104, v173
	v_mul_f32_e32 v174, v105, v174
	v_mul_f32_e32 v171, v118, v171
	v_mul_f32_e32 v172, v119, v172
	v_mul_f32_e32 v173, v120, v173
	v_mul_f32_e32 v174, v121, v174
	v_cvt_pk_bf16_f32 v179, v171, v171
	v_cvt_pk_bf16_f32 v180, v172, v172
	v_cvt_pk_bf16_f32 v181, v173, v173
	v_cvt_pk_bf16_f32 v182, v174, v174
	global_store_short v162, v179, s[66:67]
	global_store_short v163, v180, s[66:67]
	global_store_short v164, v181, s[66:67]
	global_store_short v165, v182, s[66:67]
	s_add_u32 s66, s66, 0xb000
	s_addc_u32 s67, s67, 0
	v_mul_f32_e32 v171, 0xbfb8aa3b, v106
	v_mul_f32_e32 v172, 0xbfb8aa3b, v107
	v_mul_f32_e32 v173, 0xbfb8aa3b, v108
	v_mul_f32_e32 v174, 0xbfb8aa3b, v109
	v_exp_f32_e32 v171, v171
	v_exp_f32_e32 v172, v172
	v_exp_f32_e32 v173, v173
	v_exp_f32_e32 v174, v174
	s_nop 0
	v_add_f32_e32 v171, 1.0, v171
	v_add_f32_e32 v172, 1.0, v172
	v_add_f32_e32 v173, 1.0, v173
	v_add_f32_e32 v174, 1.0, v174
	v_rcp_f32_e32 v171, v171
	v_rcp_f32_e32 v172, v172
	v_rcp_f32_e32 v173, v173
	v_rcp_f32_e32 v174, v174
	s_nop 0
	v_mul_f32_e32 v171, v106, v171
	v_mul_f32_e32 v172, v107, v172
	v_mul_f32_e32 v173, v108, v173
	v_mul_f32_e32 v174, v109, v174
	v_mul_f32_e32 v171, v122, v171
	v_mul_f32_e32 v172, v123, v172
	v_mul_f32_e32 v173, v124, v173
	v_mul_f32_e32 v174, v125, v174
	v_cvt_pk_bf16_f32 v179, v171, v171
	v_cvt_pk_bf16_f32 v180, v172, v172
	v_cvt_pk_bf16_f32 v181, v173, v173
	v_cvt_pk_bf16_f32 v182, v174, v174
	global_store_short v162, v179, s[66:67]
	global_store_short v163, v180, s[66:67]
	global_store_short v164, v181, s[66:67]
	global_store_short v165, v182, s[66:67]
	s_add_u32 s66, s66, 0xb000
	s_addc_u32 s67, s67, 0
	v_mul_f32_e32 v171, 0xbfb8aa3b, v110
	v_mul_f32_e32 v172, 0xbfb8aa3b, v111
	v_mul_f32_e32 v173, 0xbfb8aa3b, v112
	v_mul_f32_e32 v174, 0xbfb8aa3b, v113
	v_exp_f32_e32 v171, v171
	v_exp_f32_e32 v172, v172
	v_exp_f32_e32 v173, v173
	v_exp_f32_e32 v174, v174
	s_nop 0
	v_add_f32_e32 v171, 1.0, v171
	v_add_f32_e32 v172, 1.0, v172
	v_add_f32_e32 v173, 1.0, v173
	v_add_f32_e32 v174, 1.0, v174
	v_rcp_f32_e32 v171, v171
	v_rcp_f32_e32 v172, v172
	v_rcp_f32_e32 v173, v173
	v_rcp_f32_e32 v174, v174
	s_nop 0
	v_mul_f32_e32 v171, v110, v171
	v_mul_f32_e32 v172, v111, v172
	v_mul_f32_e32 v173, v112, v173
	v_mul_f32_e32 v174, v113, v174
	v_mul_f32_e32 v171, v126, v171
	v_mul_f32_e32 v172, v127, v172
	v_mul_f32_e32 v173, v128, v173
	v_mul_f32_e32 v174, v129, v174
	v_cvt_pk_bf16_f32 v179, v171, v171
	v_cvt_pk_bf16_f32 v180, v172, v172
	v_cvt_pk_bf16_f32 v181, v173, v173
	v_cvt_pk_bf16_f32 v182, v174, v174
	global_store_short v162, v179, s[66:67]
	global_store_short v163, v180, s[66:67]
	global_store_short v164, v181, s[66:67]
	global_store_short v165, v182, s[66:67]
	v_readlane_b32 s62, v246, 14
	s_nop 0
	s_add_i32 s2, s2, s62
	s_branch .Lhw_ffnup_dloop

.Lhw_ffnup_sloop:
	s_sub_i32 s62, 0x108, s64
	s_lshl_b32 s62, s62, 1
	s_cmp_ge_u32 s2, s62
	s_cbranch_scc1 .Lhw_ffnup_exit
	s_lshr_b32 s63, s2, 1
	s_add_i32 s63, s63, s64
	s_mul_i32 s6, s63, 745
	s_lshr_b32 s6, s6, 16
	s_mul_i32 s14, s6, 88
	s_sub_i32 s14, s63, s14
	v_readlane_b32 s13, v246, 16
	s_lshl_b32 s6, s6, 2
	s_and_b32 s12, s14, 3
	s_add_i32 s6, s6, s12
	s_add_i32 s6, s6, s13
	s_lshl_b32 s6, s6, 7
	s_lshr_b32 s14, s14, 2
	s_lshl_b32 s14, s14, 8
	s_and_b32 s12, s2, 1
	s_lshl_b32 s12, s12, 7
	s_add_i32 s14, s14, s12
	s_lshl_b32 vcc_lo, s6, 11
	s_add_u32 s66, s10, vcc_lo
	s_addc_u32 s67, s11, 0
	s_lshl_b32 vcc_lo, s14, 11
	s_add_u32 s12, s0, vcc_lo
	s_addc_u32 s13, s1, 0
	s_barrier
	s_add_u32 m0, s65, 0x0
	s_nop 0
	global_load_lds_dwordx4 v160, s[66:67]
	s_add_u32 m0, s65, 0x1000
	s_nop 0
	global_load_lds_dwordx4 v161, s[66:67]
	s_add_u32 m0, s65, 0x2000
	s_nop 0
	global_load_lds_dwordx4 v160, s[12:13]
	s_add_u32 m0, s65, 0x3000
	s_nop 0
	global_load_lds_dwordx4 v161, s[12:13]
	s_add_u32 s66, s66, 64
	s_addc_u32 s67, s67, 0
	s_add_u32 s12, s12, 64
	s_addc_u32 s13, s13, 0
	s_add_u32 m0, s65, 0x6000
	s_nop 0
	global_load_lds_dwordx4 v160, s[66:67]
	s_add_u32 m0, s65, 0x7000
	s_nop 0
	global_load_lds_dwordx4 v161, s[66:67]
	s_add_u32 m0, s65, 0x8000
	s_nop 0
	global_load_lds_dwordx4 v160, s[12:13]
	s_add_u32 m0, s65, 0x9000
	s_nop 0
	global_load_lds_dwordx4 v161, s[12:13]
	s_add_u32 s66, s66, 64
	s_addc_u32 s67, s67, 0
	s_add_u32 s12, s12, 64
	s_addc_u32 s13, s13, 0
	v_mov_b32_e32 v2, 0
	v_mov_b32_e32 v3, 0
	v_mov_b32_e32 v4, 0
	v_mov_b32_e32 v5, 0
	v_mov_b32_e32 v6, 0
	v_mov_b32_e32 v7, 0
	v_mov_b32_e32 v8, 0
	v_mov_b32_e32 v9, 0
	v_mov_b32_e32 v10, 0
	v_mov_b32_e32 v11, 0
	v_mov_b32_e32 v12, 0
	v_mov_b32_e32 v13, 0
	v_mov_b32_e32 v14, 0
	v_mov_b32_e32 v15, 0
	v_mov_b32_e32 v16, 0
	v_mov_b32_e32 v17, 0
	v_mov_b32_e32 v18, 0
	v_mov_b32_e32 v19, 0
	v_mov_b32_e32 v20, 0
	v_mov_b32_e32 v21, 0
	v_mov_b32_e32 v22, 0
	v_mov_b32_e32 v23, 0
	v_mov_b32_e32 v24, 0
	v_mov_b32_e32 v25, 0
	v_mov_b32_e32 v26, 0
	v_mov_b32_e32 v27, 0
	v_mov_b32_e32 v28, 0
	v_mov_b32_e32 v29, 0
	v_mov_b32_e32 v30, 0
	v_mov_b32_e32 v31, 0
	v_mov_b32_e32 v32, 0
	v_mov_b32_e32 v33, 0
	v_mov_b32_e32 v34, 0
	v_mov_b32_e32 v35, 0
	v_mov_b32_e32 v36, 0
	v_mov_b32_e32 v37, 0
	v_mov_b32_e32 v38, 0
	v_mov_b32_e32 v39, 0
	v_mov_b32_e32 v40, 0
	v_mov_b32_e32 v41, 0
	v_mov_b32_e32 v42, 0
	v_mov_b32_e32 v43, 0
	v_mov_b32_e32 v44, 0
	v_mov_b32_e32 v45, 0
	v_mov_b32_e32 v46, 0
	v_mov_b32_e32 v47, 0
	v_mov_b32_e32 v48, 0
	v_mov_b32_e32 v49, 0
	v_mov_b32_e32 v50, 0
	v_mov_b32_e32 v51, 0
	v_mov_b32_e32 v52, 0
	v_mov_b32_e32 v53, 0
	v_mov_b32_e32 v54, 0
	v_mov_b32_e32 v55, 0
	v_mov_b32_e32 v56, 0
	v_mov_b32_e32 v57, 0
	v_mov_b32_e32 v58, 0
	v_mov_b32_e32 v59, 0
	v_mov_b32_e32 v60, 0
	v_mov_b32_e32 v61, 0
	v_mov_b32_e32 v62, 0
	v_mov_b32_e32 v63, 0
	v_mov_b32_e32 v64, 0
	v_mov_b32_e32 v65, 0
	s_mov_b32 s59, 10
.Lhw_ffnup_s_loop:
	s_waitcnt vmcnt(4)
	s_barrier
	ds_read_b128 v[130:133], v154 offset:16
	ds_read_b128 v[138:141], v156 offset:8208
	ds_read_b128 v[142:145], v156 offset:10256
	ds_read_b128 v[134:137], v154 offset:2064
	s_waitcnt lgkmcnt(2)
	v_mfma_f32_32x32x16_bf16 v[2:17], v[130:133], v[138:141], v[2:17]
	ds_read_b128 v[212:215], v155 offset:16
	s_add_u32 m0, s65, 0xc000
	s_waitcnt lgkmcnt(2)
	v_mfma_f32_32x32x16_bf16 v[18:33], v[130:133], v[142:145], v[18:33]
	ds_read_b128 v[220:223], v157 offset:8208
	global_load_lds_dwordx4 v160, s[66:67]
	s_waitcnt lgkmcnt(2)
	v_mfma_f32_32x32x16_bf16 v[34:49], v[134:137], v[138:141], v[34:49]
	ds_read_b128 v[224:227], v157 offset:10256
	s_add_u32 m0, s65, 0xd000
	s_waitcnt lgkmcnt(3)
	v_mfma_f32_32x32x16_bf16 v[50:65], v[134:137], v[142:145], v[50:65]
	ds_read_b128 v[216:219], v155 offset:2064
	global_load_lds_dwordx4 v161, s[66:67]
	s_waitcnt lgkmcnt(2)
	v_mfma_f32_32x32x16_bf16 v[2:17], v[212:215], v[220:223], v[2:17]
	s_add_u32 m0, s65, 0xe000
	s_waitcnt lgkmcnt(1)
	v_mfma_f32_32x32x16_bf16 v[18:33], v[212:215], v[224:227], v[18:33]
	global_load_lds_dwordx4 v160, s[12:13]
	s_waitcnt lgkmcnt(0)
	v_mfma_f32_32x32x16_bf16 v[34:49], v[216:219], v[220:223], v[34:49]
	s_add_u32 m0, s65, 0xf000
	s_waitcnt lgkmcnt(0)
	v_mfma_f32_32x32x16_bf16 v[50:65], v[216:219], v[224:227], v[50:65]
	global_load_lds_dwordx4 v161, s[12:13]
	s_add_u32 s66, s66, 64
	s_addc_u32 s67, s67, 0
	s_add_u32 s12, s12, 64
	s_addc_u32 s13, s13, 0
	s_waitcnt vmcnt(4)
	s_barrier
	ds_read_b128 v[130:133], v154 offset:24592
	ds_read_b128 v[138:141], v156 offset:32784
	ds_read_b128 v[142:145], v156 offset:34832
	ds_read_b128 v[134:137], v154 offset:26640
	s_waitcnt lgkmcnt(2)
	v_mfma_f32_32x32x16_bf16 v[2:17], v[130:133], v[138:141], v[2:17]
	ds_read_b128 v[212:215], v155 offset:24592
	s_add_u32 m0, s65, 0x0
	s_waitcnt lgkmcnt(2)
	v_mfma_f32_32x32x16_bf16 v[18:33], v[130:133], v[142:145], v[18:33]
	ds_read_b128 v[220:223], v157 offset:32784
	global_load_lds_dwordx4 v160, s[66:67]
	s_waitcnt lgkmcnt(2)
	v_mfma_f32_32x32x16_bf16 v[34:49], v[134:137], v[138:141], v[34:49]
	ds_read_b128 v[224:227], v157 offset:34832
	s_add_u32 m0, s65, 0x1000
	s_waitcnt lgkmcnt(3)
	v_mfma_f32_32x32x16_bf16 v[50:65], v[134:137], v[142:145], v[50:65]
	ds_read_b128 v[216:219], v155 offset:26640
	global_load_lds_dwordx4 v161, s[66:67]
	s_waitcnt lgkmcnt(2)
	v_mfma_f32_32x32x16_bf16 v[2:17], v[212:215], v[220:223], v[2:17]
	s_add_u32 m0, s65, 0x2000
	s_waitcnt lgkmcnt(1)
	v_mfma_f32_32x32x16_bf16 v[18:33], v[212:215], v[224:227], v[18:33]
	global_load_lds_dwordx4 v160, s[12:13]
	s_waitcnt lgkmcnt(0)
	v_mfma_f32_32x32x16_bf16 v[34:49], v[216:219], v[220:223], v[34:49]
	s_add_u32 m0, s65, 0x3000
	s_waitcnt lgkmcnt(0)
	v_mfma_f32_32x32x16_bf16 v[50:65], v[216:219], v[224:227], v[50:65]
	global_load_lds_dwordx4 v161, s[12:13]
	s_add_u32 s66, s66, 64
	s_addc_u32 s67, s67, 0
	s_add_u32 s12, s12, 64
	s_addc_u32 s13, s13, 0
	s_waitcnt vmcnt(4)
	s_barrier
	ds_read_b128 v[130:133], v154 offset:49168
	ds_read_b128 v[138:141], v156 offset:57360
	ds_read_b128 v[142:145], v156 offset:59408
	ds_read_b128 v[134:137], v154 offset:51216
	s_waitcnt lgkmcnt(2)
	v_mfma_f32_32x32x16_bf16 v[2:17], v[130:133], v[138:141], v[2:17]
	ds_read_b128 v[212:215], v155 offset:49168
	s_add_u32 m0, s65, 0x6000
	s_waitcnt lgkmcnt(2)
	v_mfma_f32_32x32x16_bf16 v[18:33], v[130:133], v[142:145], v[18:33]
	ds_read_b128 v[220:223], v157 offset:57360
	global_load_lds_dwordx4 v160, s[66:67]
	s_waitcnt lgkmcnt(2)
	v_mfma_f32_32x32x16_bf16 v[34:49], v[134:137], v[138:141], v[34:49]
	ds_read_b128 v[224:227], v157 offset:59408
	s_add_u32 m0, s65, 0x7000
	s_waitcnt lgkmcnt(3)
	v_mfma_f32_32x32x16_bf16 v[50:65], v[134:137], v[142:145], v[50:65]
	ds_read_b128 v[216:219], v155 offset:51216
	global_load_lds_dwordx4 v161, s[66:67]
	s_waitcnt lgkmcnt(2)
	v_mfma_f32_32x32x16_bf16 v[2:17], v[212:215], v[220:223], v[2:17]
	s_add_u32 m0, s65, 0x8000
	s_waitcnt lgkmcnt(1)
	v_mfma_f32_32x32x16_bf16 v[18:33], v[212:215], v[224:227], v[18:33]
	global_load_lds_dwordx4 v160, s[12:13]
	s_waitcnt lgkmcnt(0)
	v_mfma_f32_32x32x16_bf16 v[34:49], v[216:219], v[220:223], v[34:49]
	s_add_u32 m0, s65, 0x9000
	s_waitcnt lgkmcnt(0)
	v_mfma_f32_32x32x16_bf16 v[50:65], v[216:219], v[224:227], v[50:65]
	global_load_lds_dwordx4 v161, s[12:13]
	s_add_u32 s66, s66, 64
	s_addc_u32 s67, s67, 0
	s_add_u32 s12, s12, 64
	s_addc_u32 s13, s13, 0
	s_sub_u32 s59, s59, 1
	s_cmp_lg_u32 s59, 0
	s_cbranch_scc1 .Lhw_ffnup_s_loop
	s_waitcnt vmcnt(4)
	s_barrier
	ds_read_b128 v[130:133], v154 offset:16
	ds_read_b128 v[138:141], v156 offset:8208
	ds_read_b128 v[142:145], v156 offset:10256
	ds_read_b128 v[134:137], v154 offset:2064
	s_waitcnt lgkmcnt(2)
	v_mfma_f32_32x32x16_bf16 v[2:17], v[130:133], v[138:141], v[2:17]
	ds_read_b128 v[212:215], v155 offset:16
	s_waitcnt lgkmcnt(2)
	v_mfma_f32_32x32x16_bf16 v[18:33], v[130:133], v[142:145], v[18:33]
	ds_read_b128 v[220:223], v157 offset:8208
	s_waitcnt lgkmcnt(2)
	v_mfma_f32_32x32x16_bf16 v[34:49], v[134:137], v[138:141], v[34:49]
	ds_read_b128 v[224:227], v157 offset:10256
	s_waitcnt lgkmcnt(3)
	v_mfma_f32_32x32x16_bf16 v[50:65], v[134:137], v[142:145], v[50:65]
	ds_read_b128 v[216:219], v155 offset:2064
	s_waitcnt lgkmcnt(2)
	v_mfma_f32_32x32x16_bf16 v[2:17], v[212:215], v[220:223], v[2:17]
	s_waitcnt lgkmcnt(1)
	v_mfma_f32_32x32x16_bf16 v[18:33], v[212:215], v[224:227], v[18:33]
	s_waitcnt lgkmcnt(0)
	v_mfma_f32_32x32x16_bf16 v[34:49], v[216:219], v[220:223], v[34:49]
	s_waitcnt lgkmcnt(0)
	v_mfma_f32_32x32x16_bf16 v[50:65], v[216:219], v[224:227], v[50:65]
	s_waitcnt vmcnt(0)
	s_barrier
	ds_read_b128 v[130:133], v154 offset:24592
	ds_read_b128 v[138:141], v156 offset:32784
	ds_read_b128 v[142:145], v156 offset:34832
	ds_read_b128 v[134:137], v154 offset:26640
	s_waitcnt lgkmcnt(2)
	v_mfma_f32_32x32x16_bf16 v[2:17], v[130:133], v[138:141], v[2:17]
	ds_read_b128 v[212:215], v155 offset:24592
	s_waitcnt lgkmcnt(2)
	v_mfma_f32_32x32x16_bf16 v[18:33], v[130:133], v[142:145], v[18:33]
	ds_read_b128 v[220:223], v157 offset:32784
	s_waitcnt lgkmcnt(2)
	v_mfma_f32_32x32x16_bf16 v[34:49], v[134:137], v[138:141], v[34:49]
	ds_read_b128 v[224:227], v157 offset:34832
	s_waitcnt lgkmcnt(3)
	v_mfma_f32_32x32x16_bf16 v[50:65], v[134:137], v[142:145], v[50:65]
	ds_read_b128 v[216:219], v155 offset:26640
	s_waitcnt lgkmcnt(2)
	v_mfma_f32_32x32x16_bf16 v[2:17], v[212:215], v[220:223], v[2:17]
	s_waitcnt lgkmcnt(1)
	v_mfma_f32_32x32x16_bf16 v[18:33], v[212:215], v[224:227], v[18:33]
	s_waitcnt lgkmcnt(0)
	v_mfma_f32_32x32x16_bf16 v[34:49], v[216:219], v[220:223], v[34:49]
	s_waitcnt lgkmcnt(0)
	v_mfma_f32_32x32x16_bf16 v[50:65], v[216:219], v[224:227], v[50:65]
	s_nop 7
	s_nop 7
	s_mul_i32 vcc_lo, s6, 0x1600
	s_add_u32 s66, s8, vcc_lo
	s_addc_u32 s67, s9, 0
	s_add_u32 s66, s66, s14
	s_addc_u32 s67, s67, 0
	v_mul_f32_e32 v171, 0xbfb8aa3b, v2
	v_mul_f32_e32 v172, 0xbfb8aa3b, v3
	v_mul_f32_e32 v173, 0xbfb8aa3b, v4
	v_mul_f32_e32 v174, 0xbfb8aa3b, v5
	v_exp_f32_e32 v171, v171
	v_exp_f32_e32 v172, v172
	v_exp_f32_e32 v173, v173
	v_exp_f32_e32 v174, v174
	s_nop 0
	v_add_f32_e32 v171, 1.0, v171
	v_add_f32_e32 v172, 1.0, v172
	v_add_f32_e32 v173, 1.0, v173
	v_add_f32_e32 v174, 1.0, v174
	v_rcp_f32_e32 v171, v171
	v_rcp_f32_e32 v172, v172
	v_rcp_f32_e32 v173, v173
	v_rcp_f32_e32 v174, v174
	s_nop 0
	v_mul_f32_e32 v171, v2, v171
	v_mul_f32_e32 v172, v3, v172
	v_mul_f32_e32 v173, v4, v173
	v_mul_f32_e32 v174, v5, v174
	v_mul_f32_e32 v171, v18, v171
	v_mul_f32_e32 v172, v19, v172
	v_mul_f32_e32 v173, v20, v173
	v_mul_f32_e32 v174, v21, v174
	v_cvt_pk_bf16_f32 v179, v171, v171
	v_cvt_pk_bf16_f32 v180, v172, v172
	v_cvt_pk_bf16_f32 v181, v173, v173
	v_cvt_pk_bf16_f32 v182, v174, v174
	global_store_short v162, v179, s[66:67]
	global_store_short v163, v180, s[66:67]
	global_store_short v164, v181, s[66:67]
	global_store_short v165, v182, s[66:67]
	s_add_u32 s66, s66, 0xb000
	s_addc_u32 s67, s67, 0
	v_mul_f32_e32 v171, 0xbfb8aa3b, v6
	v_mul_f32_e32 v172, 0xbfb8aa3b, v7
	v_mul_f32_e32 v173, 0xbfb8aa3b, v8
	v_mul_f32_e32 v174, 0xbfb8aa3b, v9
	v_exp_f32_e32 v171, v171
	v_exp_f32_e32 v172, v172
	v_exp_f32_e32 v173, v173
	v_exp_f32_e32 v174, v174
	s_nop 0
	v_add_f32_e32 v171, 1.0, v171
	v_add_f32_e32 v172, 1.0, v172
	v_add_f32_e32 v173, 1.0, v173
	v_add_f32_e32 v174, 1.0, v174
	v_rcp_f32_e32 v171, v171
	v_rcp_f32_e32 v172, v172
	v_rcp_f32_e32 v173, v173
	v_rcp_f32_e32 v174, v174
	s_nop 0
	v_mul_f32_e32 v171, v6, v171
	v_mul_f32_e32 v172, v7, v172
	v_mul_f32_e32 v173, v8, v173
	v_mul_f32_e32 v174, v9, v174
	v_mul_f32_e32 v171, v22, v171
	v_mul_f32_e32 v172, v23, v172
	v_mul_f32_e32 v173, v24, v173
	v_mul_f32_e32 v174, v25, v174
	v_cvt_pk_bf16_f32 v179, v171, v171
	v_cvt_pk_bf16_f32 v180, v172, v172
	v_cvt_pk_bf16_f32 v181, v173, v173
	v_cvt_pk_bf16_f32 v182, v174, v174
	global_store_short v162, v179, s[66:67]
	global_store_short v163, v180, s[66:67]
	global_store_short v164, v181, s[66:67]
	global_store_short v165, v182, s[66:67]
	s_add_u32 s66, s66, 0xb000
	s_addc_u32 s67, s67, 0
	v_mul_f32_e32 v171, 0xbfb8aa3b, v10
	v_mul_f32_e32 v172, 0xbfb8aa3b, v11
	v_mul_f32_e32 v173, 0xbfb8aa3b, v12
	v_mul_f32_e32 v174, 0xbfb8aa3b, v13
	v_exp_f32_e32 v171, v171
	v_exp_f32_e32 v172, v172
	v_exp_f32_e32 v173, v173
	v_exp_f32_e32 v174, v174
	s_nop 0
	v_add_f32_e32 v171, 1.0, v171
	v_add_f32_e32 v172, 1.0, v172
	v_add_f32_e32 v173, 1.0, v173
	v_add_f32_e32 v174, 1.0, v174
	v_rcp_f32_e32 v171, v171
	v_rcp_f32_e32 v172, v172
	v_rcp_f32_e32 v173, v173
	v_rcp_f32_e32 v174, v174
	s_nop 0
	v_mul_f32_e32 v171, v10, v171
	v_mul_f32_e32 v172, v11, v172
	v_mul_f32_e32 v173, v12, v173
	v_mul_f32_e32 v174, v13, v174
	v_mul_f32_e32 v171, v26, v171
	v_mul_f32_e32 v172, v27, v172
	v_mul_f32_e32 v173, v28, v173
	v_mul_f32_e32 v174, v29, v174
	v_cvt_pk_bf16_f32 v179, v171, v171
	v_cvt_pk_bf16_f32 v180, v172, v172
	v_cvt_pk_bf16_f32 v181, v173, v173
	v_cvt_pk_bf16_f32 v182, v174, v174
	global_store_short v162, v179, s[66:67]
	global_store_short v163, v180, s[66:67]
	global_store_short v164, v181, s[66:67]
	global_store_short v165, v182, s[66:67]
	s_add_u32 s66, s66, 0xb000
	s_addc_u32 s67, s67, 0
	v_mul_f32_e32 v171, 0xbfb8aa3b, v14
	v_mul_f32_e32 v172, 0xbfb8aa3b, v15
	v_mul_f32_e32 v173, 0xbfb8aa3b, v16
	v_mul_f32_e32 v174, 0xbfb8aa3b, v17
	v_exp_f32_e32 v171, v171
	v_exp_f32_e32 v172, v172
	v_exp_f32_e32 v173, v173
	v_exp_f32_e32 v174, v174
	s_nop 0
	v_add_f32_e32 v171, 1.0, v171
	v_add_f32_e32 v172, 1.0, v172
	v_add_f32_e32 v173, 1.0, v173
	v_add_f32_e32 v174, 1.0, v174
	v_rcp_f32_e32 v171, v171
	v_rcp_f32_e32 v172, v172
	v_rcp_f32_e32 v173, v173
	v_rcp_f32_e32 v174, v174
	s_nop 0
	v_mul_f32_e32 v171, v14, v171
	v_mul_f32_e32 v172, v15, v172
	v_mul_f32_e32 v173, v16, v173
	v_mul_f32_e32 v174, v17, v174
	v_mul_f32_e32 v171, v30, v171
	v_mul_f32_e32 v172, v31, v172
	v_mul_f32_e32 v173, v32, v173
	v_mul_f32_e32 v174, v33, v174
	v_cvt_pk_bf16_f32 v179, v171, v171
	v_cvt_pk_bf16_f32 v180, v172, v172
	v_cvt_pk_bf16_f32 v181, v173, v173
	v_cvt_pk_bf16_f32 v182, v174, v174
	global_store_short v162, v179, s[66:67]
	global_store_short v163, v180, s[66:67]
	global_store_short v164, v181, s[66:67]
	global_store_short v165, v182, s[66:67]
	s_add_u32 s66, s66, 0xb000
	s_addc_u32 s67, s67, 0
	v_mul_f32_e32 v171, 0xbfb8aa3b, v34
	v_mul_f32_e32 v172, 0xbfb8aa3b, v35
	v_mul_f32_e32 v173, 0xbfb8aa3b, v36
	v_mul_f32_e32 v174, 0xbfb8aa3b, v37
	v_exp_f32_e32 v171, v171
	v_exp_f32_e32 v172, v172
	v_exp_f32_e32 v173, v173
	v_exp_f32_e32 v174, v174
	s_nop 0
	v_add_f32_e32 v171, 1.0, v171
	v_add_f32_e32 v172, 1.0, v172
	v_add_f32_e32 v173, 1.0, v173
	v_add_f32_e32 v174, 1.0, v174
	v_rcp_f32_e32 v171, v171
	v_rcp_f32_e32 v172, v172
	v_rcp_f32_e32 v173, v173
	v_rcp_f32_e32 v174, v174
	s_nop 0
	v_mul_f32_e32 v171, v34, v171
	v_mul_f32_e32 v172, v35, v172
	v_mul_f32_e32 v173, v36, v173
	v_mul_f32_e32 v174, v37, v174
	v_mul_f32_e32 v171, v50, v171
	v_mul_f32_e32 v172, v51, v172
	v_mul_f32_e32 v173, v52, v173
	v_mul_f32_e32 v174, v53, v174
	v_cvt_pk_bf16_f32 v179, v171, v171
	v_cvt_pk_bf16_f32 v180, v172, v172
	v_cvt_pk_bf16_f32 v181, v173, v173
	v_cvt_pk_bf16_f32 v182, v174, v174
	global_store_short v162, v179, s[66:67]
	global_store_short v163, v180, s[66:67]
	global_store_short v164, v181, s[66:67]
	global_store_short v165, v182, s[66:67]
	s_add_u32 s66, s66, 0xb000
	s_addc_u32 s67, s67, 0
	v_mul_f32_e32 v171, 0xbfb8aa3b, v38
	v_mul_f32_e32 v172, 0xbfb8aa3b, v39
	v_mul_f32_e32 v173, 0xbfb8aa3b, v40
	v_mul_f32_e32 v174, 0xbfb8aa3b, v41
	v_exp_f32_e32 v171, v171
	v_exp_f32_e32 v172, v172
	v_exp_f32_e32 v173, v173
	v_exp_f32_e32 v174, v174
	s_nop 0
	v_add_f32_e32 v171, 1.0, v171
	v_add_f32_e32 v172, 1.0, v172
	v_add_f32_e32 v173, 1.0, v173
	v_add_f32_e32 v174, 1.0, v174
	v_rcp_f32_e32 v171, v171
	v_rcp_f32_e32 v172, v172
	v_rcp_f32_e32 v173, v173
	v_rcp_f32_e32 v174, v174
	s_nop 0
	v_mul_f32_e32 v171, v38, v171
	v_mul_f32_e32 v172, v39, v172
	v_mul_f32_e32 v173, v40, v173
	v_mul_f32_e32 v174, v41, v174
	v_mul_f32_e32 v171, v54, v171
	v_mul_f32_e32 v172, v55, v172
	v_mul_f32_e32 v173, v56, v173
	v_mul_f32_e32 v174, v57, v174
	v_cvt_pk_bf16_f32 v179, v171, v171
	v_cvt_pk_bf16_f32 v180, v172, v172
	v_cvt_pk_bf16_f32 v181, v173, v173
	v_cvt_pk_bf16_f32 v182, v174, v174
	global_store_short v162, v179, s[66:67]
	global_store_short v163, v180, s[66:67]
	global_store_short v164, v181, s[66:67]
	global_store_short v165, v182, s[66:67]
	s_add_u32 s66, s66, 0xb000
	s_addc_u32 s67, s67, 0
	v_mul_f32_e32 v171, 0xbfb8aa3b, v42
	v_mul_f32_e32 v172, 0xbfb8aa3b, v43
	v_mul_f32_e32 v173, 0xbfb8aa3b, v44
	v_mul_f32_e32 v174, 0xbfb8aa3b, v45
	v_exp_f32_e32 v171, v171
	v_exp_f32_e32 v172, v172
	v_exp_f32_e32 v173, v173
	v_exp_f32_e32 v174, v174
	s_nop 0
	v_add_f32_e32 v171, 1.0, v171
	v_add_f32_e32 v172, 1.0, v172
	v_add_f32_e32 v173, 1.0, v173
	v_add_f32_e32 v174, 1.0, v174
	v_rcp_f32_e32 v171, v171
	v_rcp_f32_e32 v172, v172
	v_rcp_f32_e32 v173, v173
	v_rcp_f32_e32 v174, v174
	s_nop 0
	v_mul_f32_e32 v171, v42, v171
	v_mul_f32_e32 v172, v43, v172
	v_mul_f32_e32 v173, v44, v173
	v_mul_f32_e32 v174, v45, v174
	v_mul_f32_e32 v171, v58, v171
	v_mul_f32_e32 v172, v59, v172
	v_mul_f32_e32 v173, v60, v173
	v_mul_f32_e32 v174, v61, v174
	v_cvt_pk_bf16_f32 v179, v171, v171
	v_cvt_pk_bf16_f32 v180, v172, v172
	v_cvt_pk_bf16_f32 v181, v173, v173
	v_cvt_pk_bf16_f32 v182, v174, v174
	global_store_short v162, v179, s[66:67]
	global_store_short v163, v180, s[66:67]
	global_store_short v164, v181, s[66:67]
	global_store_short v165, v182, s[66:67]
	s_add_u32 s66, s66, 0xb000
	s_addc_u32 s67, s67, 0
	v_mul_f32_e32 v171, 0xbfb8aa3b, v46
	v_mul_f32_e32 v172, 0xbfb8aa3b, v47
	v_mul_f32_e32 v173, 0xbfb8aa3b, v48
	v_mul_f32_e32 v174, 0xbfb8aa3b, v49
	v_exp_f32_e32 v171, v171
	v_exp_f32_e32 v172, v172
	v_exp_f32_e32 v173, v173
	v_exp_f32_e32 v174, v174
	s_nop 0
	v_add_f32_e32 v171, 1.0, v171
	v_add_f32_e32 v172, 1.0, v172
	v_add_f32_e32 v173, 1.0, v173
	v_add_f32_e32 v174, 1.0, v174
	v_rcp_f32_e32 v171, v171
	v_rcp_f32_e32 v172, v172
	v_rcp_f32_e32 v173, v173
	v_rcp_f32_e32 v174, v174
	s_nop 0
	v_mul_f32_e32 v171, v46, v171
	v_mul_f32_e32 v172, v47, v172
	v_mul_f32_e32 v173, v48, v173
	v_mul_f32_e32 v174, v49, v174
	v_mul_f32_e32 v171, v62, v171
	v_mul_f32_e32 v172, v63, v172
	v_mul_f32_e32 v173, v64, v173
	v_mul_f32_e32 v174, v65, v174
	v_cvt_pk_bf16_f32 v179, v171, v171
	v_cvt_pk_bf16_f32 v180, v172, v172
	v_cvt_pk_bf16_f32 v181, v173, v173
	v_cvt_pk_bf16_f32 v182, v174, v174
	global_store_short v162, v179, s[66:67]
	global_store_short v163, v180, s[66:67]
	global_store_short v164, v181, s[66:67]
	global_store_short v165, v182, s[66:67]
	v_readlane_b32 s62, v246, 14
	s_nop 0
	s_add_i32 s2, s2, s62
	s_branch .Lhw_ffnup_sloop
